# G1 epilogue stores write-through (sc1) so the 403 MB P0 stream does not stay dirty in L2
# speedup vs baseline: 1.0141x; 1.0112x over previous
; #define PG8_STAGE(bufoff, gbase, voff) do { const char* _gb = (const char*)(gbase); asm volatile("" : "+s"(_gb)); _Pragma("unroll") for (int _i = 0; _i < 2; ++_i) \
;         __builtin_amdgcn_global_load_lds((const unsigned*)(_gb + (voff)[_i]), (LAS unsigned*)(lds + (bufoff) + ldsw + _i * 8192), 16, 0, 0); } while (0)
; #define PG8_LDA(dst, b, h) do { _Pragma("unroll") for (int m = 0; m < 4; ++m) _Pragma("unroll") for (int k = 0; k < 2; ++k) dst[m][k] = *(const LAS bf16x8*)(lds + PG8_SA(b, h) + aoff + m * 2048 + k * 1024); } while (0)
; #define PG8_LDB(dst, b, h) do { _Pragma("unroll") for (int n = 0; n < 2; ++n) _Pragma("unroll") for (int k = 0; k < 2; ++k) dst[n][k] = *(const LAS bf16x8*)(lds + PG8_SB(b, h) + boff + n * 2048 + k * 1024); } while (0)
; #define PG8_MMA(ai, bj, At, Bt) do { __builtin_amdgcn_s_setprio(1); _Pragma("unroll") for (int m = 0; m < 4; ++m) _Pragma("unroll") for (int n = 0; n < 2; ++n) _Pragma("unroll") for (int k = 0; k < 2; ++k) \
;         acc[ai][bj][m][n] = __builtin_amdgcn_mfma_f32_16x16x32_bf16(Bt[n][k], At[m][k], acc[ai][bj][m][n], 0, 0, 0); __builtin_amdgcn_s_setprio(0); } while (0)
; #define PG8_WAIT_L(n) asm volatile("s_waitcnt lgkmcnt(" #n ")" ::: "memory")
; #define PG8_BAR __builtin_amdgcn_s_barrier()
; #define PG8_SCHED __builtin_amdgcn_sched_barrier(0)
; template <class Epi, class Sched>
; __device__ __forceinline__ void gemm_phase(LAS unsigned char* lds, const Gemm g, const Sched& S, const Epi& E) {
;     ...
;         for (int t = 0; t < nt; t += 2) {
;             const bool last = (t == nt - 2);
;             const char* a1 = cA + (size_t)(t + 1) * kstep;
;             const char* a2 = last ? nA : cA + (size_t)(t + 2) * kstep; const char* b2 = last ? nB : cB + (size_t)(t + 2) * kstep;
;             const char* a3 = a2 + kstep; const char* b3 = b2 + kstep;
;             PG8_LDB(B0, 0, 0); PG8_SCHED; PG8_LDA(At, 0, 0); PG8_STAGE(PG8_SA(1, 1), a1 + hA, voffA);
;             PG8_WAIT_L(8); PG8_BAR; PG8_WAIT_L(0); PG8_MMA(0, 0, At, B0); PG8_BAR; PG8_SCHED;
;             PG8_LDB(B1, 0, 1); PG8_STAGE(PG8_SB(0, 0), b2, voffB);
;             PG8_BAR; PG8_WAIT_L(0); PG8_MMA(0, 1, At, B1); PG8_BAR;
;             PG8_LDA(At, 0, 1); PG8_STAGE(PG8_SA(0, 0), a2, voffA);
;             PG8_BAR; PG8_WAIT_L(0); PG8_MMA(1, 0, At, B0); PG8_BAR; PG8_SCHED;
;             PG8_STAGE(PG8_SB(0, 1), b2 + hB, voffB);
.LBB0_74:
	ds_read_b128 v[160:163], v154
	ds_read_b128 v[164:167], v154 offset:1024
	ds_read_b128 v[168:171], v154 offset:2048
	ds_read_b128 v[172:175], v154 offset:3072
	s_add_u32 s12, s10, 0x100
	s_addc_u32 s13, s11, 0
	s_cmp_eq_u32 s43, 12
	s_cselect_b32 s18, s6, s12
	s_cselect_b32 s19, s7, s13
	s_cselect_b32 s14, s40, s41
	s_cselect_b32 s15, s39, s42
	s_add_u32 s16, s18, 0x80
	s_addc_u32 s17, s19, 0
	s_add_u32 s10, s10, 0x40080
	s_addc_u32 s11, s11, 0
	s_mov_b32 m0, s28
	ds_read_b128 v[178:181], v155
	ds_read_b128 v[182:185], v155 offset:1024
	ds_read_b128 v[186:189], v155 offset:2048
	ds_read_b128 v[190:193], v155 offset:3072
	ds_read_b128 v[194:197], v155 offset:4096
	ds_read_b128 v[198:201], v155 offset:5120
	ds_read_b128 v[202:205], v155 offset:6144
	ds_read_b128 v[206:209], v155 offset:7168
	s_nop 0
	v_lshl_add_u64 v[210:211], s[10:11], 0, v[134:135]
	global_load_lds_dwordx4 v[210:211], off
	v_lshl_add_u64 v[210:211], s[10:11], 0, v[130:131]
	s_mov_b32 m0, s29
	s_nop 0
	global_load_lds_dwordx4 v[210:211], off
	s_waitcnt lgkmcnt(8)
	s_barrier
	s_waitcnt lgkmcnt(0)
	s_setprio 1
	s_waitcnt lgkmcnt(0)
	v_mfma_f32_16x16x32_bf16 v[124:127], v[160:163], v[178:181], v[124:127]
	v_mfma_f32_16x16x32_bf16 v[120:123], v[168:171], v[178:181], v[120:123]
	v_mfma_f32_16x16x32_bf16 v[116:119], v[160:163], v[186:189], v[116:119]
	v_mfma_f32_16x16x32_bf16 v[108:111], v[168:171], v[186:189], v[108:111]
	v_mfma_f32_16x16x32_bf16 v[100:103], v[160:163], v[194:197], v[100:103]
	v_mfma_f32_16x16x32_bf16 v[92:95], v[168:171], v[194:197], v[92:95]
	v_mfma_f32_16x16x32_bf16 v[84:87], v[160:163], v[202:205], v[84:87]
	v_mfma_f32_16x16x32_bf16 v[76:79], v[168:171], v[202:205], v[76:79]
	v_mfma_f32_16x16x32_bf16 v[124:127], v[164:167], v[182:185], v[124:127]
	v_mfma_f32_16x16x32_bf16 v[120:123], v[172:175], v[182:185], v[120:123]
	v_mfma_f32_16x16x32_bf16 v[116:119], v[164:167], v[190:193], v[116:119]
	v_mfma_f32_16x16x32_bf16 v[108:111], v[172:175], v[190:193], v[108:111]
	v_mfma_f32_16x16x32_bf16 v[100:103], v[164:167], v[198:201], v[100:103]
	v_mfma_f32_16x16x32_bf16 v[92:95], v[172:175], v[198:201], v[92:95]
	v_mfma_f32_16x16x32_bf16 v[84:87], v[164:167], v[206:209], v[84:87]
	v_mfma_f32_16x16x32_bf16 v[76:79], v[172:175], v[206:209], v[76:79]
	s_setprio 0
	s_barrier
	s_mov_b64 s[10:11], s[14:15]
	s_mov_b32 m0, s30
	ds_read_b128 v[210:213], v156
	ds_read_b128 v[214:217], v156 offset:1024
	ds_read_b128 v[218:221], v156 offset:2048
	ds_read_b128 v[222:225], v156 offset:3072
	s_nop 0
	v_lshl_add_u64 v[226:227], s[10:11], 0, v[132:133]
	global_load_lds_dwordx4 v[226:227], off
	v_lshl_add_u64 v[226:227], s[10:11], 0, v[128:129]
	s_mov_b32 m0, s31
	s_nop 0
	global_load_lds_dwordx4 v[226:227], off
	s_barrier
	s_waitcnt lgkmcnt(0)
	s_setprio 1
	s_waitcnt lgkmcnt(0)
	v_mfma_f32_16x16x32_bf16 v[112:115], v[210:213], v[178:181], v[112:115]
	v_mfma_f32_16x16x32_bf16 v[104:107], v[218:221], v[178:181], v[104:107]
	v_mfma_f32_16x16x32_bf16 v[96:99], v[210:213], v[186:189], v[96:99]
	v_mfma_f32_16x16x32_bf16 v[88:91], v[218:221], v[186:189], v[88:91]
	v_mfma_f32_16x16x32_bf16 v[80:83], v[210:213], v[194:197], v[80:83]
	v_mfma_f32_16x16x32_bf16 v[72:75], v[218:221], v[194:197], v[72:75]
	v_mfma_f32_16x16x32_bf16 v[68:71], v[210:213], v[202:205], v[68:71]
	v_mfma_f32_16x16x32_bf16 v[64:67], v[218:221], v[202:205], v[64:67]
	v_mfma_f32_16x16x32_bf16 v[112:115], v[214:217], v[182:185], v[112:115]
	v_mfma_f32_16x16x32_bf16 v[104:107], v[222:225], v[182:185], v[104:107]
	v_mfma_f32_16x16x32_bf16 v[96:99], v[214:217], v[190:193], v[96:99]
	v_mfma_f32_16x16x32_bf16 v[88:91], v[222:225], v[190:193], v[88:91]
	v_mfma_f32_16x16x32_bf16 v[80:83], v[214:217], v[198:201], v[80:83]
	v_mfma_f32_16x16x32_bf16 v[72:75], v[222:225], v[198:201], v[72:75]
	v_mfma_f32_16x16x32_bf16 v[68:71], v[214:217], v[206:209], v[68:71]
	v_mfma_f32_16x16x32_bf16 v[64:67], v[222:225], v[206:209], v[64:67]
	s_setprio 0
	s_mov_b64 s[10:11], s[18:19]
	s_mov_b32 m0, s3
	s_barrier
	ds_read_b128 v[178:181], v155 offset:16384
	ds_read_b128 v[182:185], v155 offset:17408
	ds_read_b128 v[186:189], v155 offset:18432
	ds_read_b128 v[190:193], v155 offset:19456
	ds_read_b128 v[194:197], v155 offset:20480
	ds_read_b128 v[198:201], v155 offset:21504
	ds_read_b128 v[202:205], v155 offset:22528
	ds_read_b128 v[206:209], v155 offset:23552
	s_nop 0
	v_lshl_add_u64 v[226:227], s[10:11], 0, v[134:135]
	global_load_lds_dwordx4 v[226:227], off
	v_lshl_add_u64 v[226:227], s[10:11], 0, v[130:131]
	s_mov_b32 m0, s22
	s_nop 0
	global_load_lds_dwordx4 v[226:227], off
	s_barrier
	s_waitcnt lgkmcnt(0)
	s_setprio 1
	s_waitcnt lgkmcnt(0)
	v_mfma_f32_16x16x32_bf16 v[60:63], v[160:163], v[178:181], v[60:63]
	v_mfma_f32_16x16x32_bf16 v[56:59], v[168:171], v[178:181], v[56:59]
	v_mfma_f32_16x16x32_bf16 v[52:55], v[160:163], v[186:189], v[52:55]
	v_mfma_f32_16x16x32_bf16 v[44:47], v[168:171], v[186:189], v[44:47]
	v_mfma_f32_16x16x32_bf16 v[36:39], v[160:163], v[194:197], v[36:39]
	v_mfma_f32_16x16x32_bf16 v[28:31], v[168:171], v[194:197], v[28:31]
	v_mfma_f32_16x16x32_bf16 v[20:23], v[160:163], v[202:205], v[20:23]
	v_mfma_f32_16x16x32_bf16 v[12:15], v[168:171], v[202:205], v[12:15]
	v_mfma_f32_16x16x32_bf16 v[60:63], v[164:167], v[182:185], v[60:63]
	v_mfma_f32_16x16x32_bf16 v[56:59], v[172:175], v[182:185], v[56:59]
	v_mfma_f32_16x16x32_bf16 v[52:55], v[164:167], v[190:193], v[52:55]
	v_mfma_f32_16x16x32_bf16 v[44:47], v[172:175], v[190:193], v[44:47]
	v_mfma_f32_16x16x32_bf16 v[36:39], v[164:167], v[198:201], v[36:39]
	v_mfma_f32_16x16x32_bf16 v[28:31], v[172:175], v[198:201], v[28:31]
	v_mfma_f32_16x16x32_bf16 v[20:23], v[164:167], v[206:209], v[20:23]
	v_mfma_f32_16x16x32_bf16 v[12:15], v[172:175], v[206:209], v[12:15]
	s_setprio 0
	s_barrier
; #define PG8_STAGE(bufoff, gbase, voff) do { const char* _gb = (const char*)(gbase); asm volatile("" : "+s"(_gb)); _Pragma("unroll") for (int _i = 0; _i < 2; ++_i) \
;         __builtin_amdgcn_global_load_lds((const unsigned*)(_gb + (voff)[_i]), (LAS unsigned*)(lds + (bufoff) + ldsw + _i * 8192), 16, 0, 0); } while (0)
; #define PG8_LDA(dst, b, h) do { _Pragma("unroll") for (int m = 0; m < 4; ++m) _Pragma("unroll") for (int k = 0; k < 2; ++k) dst[m][k] = *(const LAS bf16x8*)(lds + PG8_SA(b, h) + aoff + m * 2048 + k * 1024); } while (0)
; #define PG8_LDB(dst, b, h) do { _Pragma("unroll") for (int n = 0; n < 2; ++n) _Pragma("unroll") for (int k = 0; k < 2; ++k) dst[n][k] = *(const LAS bf16x8*)(lds + PG8_SB(b, h) + boff + n * 2048 + k * 1024); } while (0)
; #define PG8_MMA(ai, bj, At, Bt) do { __builtin_amdgcn_s_setprio(1); _Pragma("unroll") for (int m = 0; m < 4; ++m) _Pragma("unroll") for (int n = 0; n < 2; ++n) _Pragma("unroll") for (int k = 0; k < 2; ++k) \
;         acc[ai][bj][m][n] = __builtin_amdgcn_mfma_f32_16x16x32_bf16(Bt[n][k], At[m][k], acc[ai][bj][m][n], 0, 0, 0); __builtin_amdgcn_s_setprio(0); } while (0)
; #define PG8_WAIT_V(n) asm volatile("s_waitcnt vmcnt(" #n ")" ::: "memory")
; #define PG8_WAIT_L(n) asm volatile("s_waitcnt lgkmcnt(" #n ")" ::: "memory")
; #define PG8_BAR __builtin_amdgcn_s_barrier()
; #define PG8_SCHED __builtin_amdgcn_sched_barrier(0)
; template <class Epi, class Sched>
; __device__ __forceinline__ void gemm_phase(LAS unsigned char* lds, const Gemm g, const Sched& S, const Epi& E) {
;     ...
;             PG8_STAGE(PG8_SB(0, 1), b2 + hB, voffB);
;             PG8_WAIT_V(6); PG8_BAR; PG8_MMA(1, 1, At, B1); PG8_BAR;
;             PG8_LDB(B0, 1, 0); PG8_SCHED; PG8_LDA(At, 1, 0); PG8_STAGE(PG8_SA(0, 1), a2 + hA, voffA);
;             PG8_WAIT_L(8); PG8_BAR; PG8_WAIT_L(0); PG8_MMA(0, 0, At, B0); PG8_BAR; PG8_SCHED;
;             PG8_LDB(B1, 1, 1); PG8_STAGE(PG8_SB(1, 0), b3, voffB);
;             PG8_BAR; PG8_WAIT_L(0); PG8_MMA(0, 1, At, B1); PG8_BAR;
;             PG8_LDA(At, 1, 1); PG8_STAGE(PG8_SA(1, 0), a3, voffA);
;             PG8_BAR; PG8_WAIT_L(0); PG8_MMA(1, 0, At, B0); PG8_BAR; PG8_SCHED;
	s_add_u32 s10, s14, 0x40000
	s_addc_u32 s11, s15, 0
	s_mov_b32 m0, s33
	s_nop 0
	v_lshl_add_u64 v[160:161], s[10:11], 0, v[132:133]
	global_load_lds_dwordx4 v[160:161], off
	v_lshl_add_u64 v[160:161], s[10:11], 0, v[128:129]
	s_mov_b32 m0, s34
	s_nop 0
	global_load_lds_dwordx4 v[160:161], off
	s_waitcnt vmcnt(6)
	s_barrier
	s_setprio 1
	v_mfma_f32_16x16x32_bf16 v[48:51], v[210:213], v[178:181], v[48:51]
	v_mfma_f32_16x16x32_bf16 v[40:43], v[218:221], v[178:181], v[40:43]
	v_mfma_f32_16x16x32_bf16 v[32:35], v[210:213], v[186:189], v[32:35]
	v_mfma_f32_16x16x32_bf16 v[24:27], v[218:221], v[186:189], v[24:27]
	v_mfma_f32_16x16x32_bf16 v[16:19], v[210:213], v[194:197], v[16:19]
	v_mfma_f32_16x16x32_bf16 v[8:11], v[218:221], v[194:197], v[8:11]
	v_mfma_f32_16x16x32_bf16 v[4:7], v[210:213], v[202:205], v[4:7]
	v_mfma_f32_16x16x32_bf16 v[0:3], v[218:221], v[202:205], v[0:3]
	v_mfma_f32_16x16x32_bf16 v[48:51], v[214:217], v[182:185], v[48:51]
	v_mfma_f32_16x16x32_bf16 v[40:43], v[222:225], v[182:185], v[40:43]
	v_mfma_f32_16x16x32_bf16 v[32:35], v[214:217], v[190:193], v[32:35]
	v_mfma_f32_16x16x32_bf16 v[24:27], v[222:225], v[190:193], v[24:27]
	v_mfma_f32_16x16x32_bf16 v[16:19], v[214:217], v[198:201], v[16:19]
	v_mfma_f32_16x16x32_bf16 v[8:11], v[222:225], v[198:201], v[8:11]
	v_mfma_f32_16x16x32_bf16 v[4:7], v[214:217], v[206:209], v[4:7]
	v_mfma_f32_16x16x32_bf16 v[0:3], v[222:225], v[206:209], v[0:3]
	s_setprio 0
	s_barrier
	ds_read_b128 v[160:163], v158
	ds_read_b128 v[164:167], v158 offset:1024
	ds_read_b128 v[168:171], v158 offset:2048
	ds_read_b128 v[172:175], v158 offset:3072
	s_add_u32 s10, s18, 0x40000
	s_addc_u32 s11, s19, 0
	s_mov_b32 m0, s23
	ds_read_b128 v[178:181], v155 offset:32768
	ds_read_b128 v[182:185], v155 offset:33792
	ds_read_b128 v[186:189], v155 offset:34816
	ds_read_b128 v[190:193], v155 offset:35840
	ds_read_b128 v[194:197], v155 offset:36864
	ds_read_b128 v[198:201], v155 offset:37888
	ds_read_b128 v[202:205], v155 offset:38912
	ds_read_b128 v[206:209], v155 offset:39936
	s_nop 0
	v_lshl_add_u64 v[210:211], s[10:11], 0, v[134:135]
	global_load_lds_dwordx4 v[210:211], off
	v_lshl_add_u64 v[210:211], s[10:11], 0, v[130:131]
	s_mov_b32 m0, s24
	s_nop 0
	global_load_lds_dwordx4 v[210:211], off
	s_waitcnt lgkmcnt(8)
	s_barrier
	s_waitcnt lgkmcnt(0)
	s_setprio 1
	s_waitcnt lgkmcnt(0)
	v_mfma_f32_16x16x32_bf16 v[124:127], v[160:163], v[178:181], v[124:127]
	v_mfma_f32_16x16x32_bf16 v[120:123], v[168:171], v[178:181], v[120:123]
	v_mfma_f32_16x16x32_bf16 v[116:119], v[160:163], v[186:189], v[116:119]
	v_mfma_f32_16x16x32_bf16 v[108:111], v[168:171], v[186:189], v[108:111]
	v_mfma_f32_16x16x32_bf16 v[100:103], v[160:163], v[194:197], v[100:103]
	v_mfma_f32_16x16x32_bf16 v[92:95], v[168:171], v[194:197], v[92:95]
	v_mfma_f32_16x16x32_bf16 v[84:87], v[160:163], v[202:205], v[84:87]
	v_mfma_f32_16x16x32_bf16 v[76:79], v[168:171], v[202:205], v[76:79]
	v_mfma_f32_16x16x32_bf16 v[124:127], v[164:167], v[182:185], v[124:127]
	v_mfma_f32_16x16x32_bf16 v[120:123], v[172:175], v[182:185], v[120:123]
	v_mfma_f32_16x16x32_bf16 v[116:119], v[164:167], v[190:193], v[116:119]
	v_mfma_f32_16x16x32_bf16 v[108:111], v[172:175], v[190:193], v[108:111]
	v_mfma_f32_16x16x32_bf16 v[100:103], v[164:167], v[198:201], v[100:103]
	v_mfma_f32_16x16x32_bf16 v[92:95], v[172:175], v[198:201], v[92:95]
	v_mfma_f32_16x16x32_bf16 v[84:87], v[164:167], v[206:209], v[84:87]
	v_mfma_f32_16x16x32_bf16 v[76:79], v[172:175], v[206:209], v[76:79]
	s_setprio 0
	s_barrier
	s_add_u32 s10, s14, 0x80
	s_addc_u32 s11, s15, 0
	s_add_i32 s18, s35, s21
	ds_read_b128 v[210:213], v159
	ds_read_b128 v[214:217], v159 offset:1024
	ds_read_b128 v[218:221], v159 offset:2048
	ds_read_b128 v[222:225], v159 offset:3072
	s_mov_b32 m0, s18
	v_lshl_add_u64 v[226:227], s[10:11], 0, v[132:133]
	global_load_lds_dwordx4 v[226:227], off
	v_lshl_add_u64 v[226:227], s[10:11], 0, v[128:129]
	s_add_i32 m0, s18, 0x2000
	s_nop 0
	global_load_lds_dwordx4 v[226:227], off
	s_barrier
	s_waitcnt lgkmcnt(0)
	s_setprio 1
	s_waitcnt lgkmcnt(0)
	v_mfma_f32_16x16x32_bf16 v[112:115], v[210:213], v[178:181], v[112:115]
	v_mfma_f32_16x16x32_bf16 v[104:107], v[218:221], v[178:181], v[104:107]
	v_mfma_f32_16x16x32_bf16 v[96:99], v[210:213], v[186:189], v[96:99]
	v_mfma_f32_16x16x32_bf16 v[88:91], v[218:221], v[186:189], v[88:91]
	v_mfma_f32_16x16x32_bf16 v[80:83], v[210:213], v[194:197], v[80:83]
	v_mfma_f32_16x16x32_bf16 v[72:75], v[218:221], v[194:197], v[72:75]
	v_mfma_f32_16x16x32_bf16 v[68:71], v[210:213], v[202:205], v[68:71]
	v_mfma_f32_16x16x32_bf16 v[64:67], v[218:221], v[202:205], v[64:67]
	v_mfma_f32_16x16x32_bf16 v[112:115], v[214:217], v[182:185], v[112:115]
	v_mfma_f32_16x16x32_bf16 v[104:107], v[222:225], v[182:185], v[104:107]
	v_mfma_f32_16x16x32_bf16 v[96:99], v[214:217], v[190:193], v[96:99]
	v_mfma_f32_16x16x32_bf16 v[88:91], v[222:225], v[190:193], v[88:91]
	v_mfma_f32_16x16x32_bf16 v[80:83], v[214:217], v[198:201], v[80:83]
	v_mfma_f32_16x16x32_bf16 v[72:75], v[222:225], v[198:201], v[72:75]
	v_mfma_f32_16x16x32_bf16 v[68:71], v[214:217], v[206:209], v[68:71]
	v_mfma_f32_16x16x32_bf16 v[64:67], v[222:225], v[206:209], v[64:67]
	s_setprio 0
	s_mov_b32 m0, s25
	s_barrier
	ds_read_b128 v[178:181], v155 offset:49152
	ds_read_b128 v[182:185], v155 offset:50176
	ds_read_b128 v[186:189], v155 offset:51200
	ds_read_b128 v[190:193], v155 offset:52224
	ds_read_b128 v[194:197], v155 offset:53248
	ds_read_b128 v[198:201], v155 offset:54272
	ds_read_b128 v[202:205], v155 offset:55296
	ds_read_b128 v[206:209], v155 offset:56320
	s_nop 0
	v_lshl_add_u64 v[226:227], s[16:17], 0, v[134:135]
	global_load_lds_dwordx4 v[226:227], off
	v_lshl_add_u64 v[226:227], s[16:17], 0, v[130:131]
	s_mov_b32 m0, s26
	s_nop 0
	global_load_lds_dwordx4 v[226:227], off
	s_barrier
; __device__ __forceinline__ unsigned cvt_pk(float lo, float hi) { unsigned r; asm volatile("v_cvt_pk_bf16_f32 %0, %1, %2" : "=v"(r) : "v"(lo), "v"(hi)); return r; }
; #define PG8_STAGE(bufoff, gbase, voff) do { const char* _gb = (const char*)(gbase); asm volatile("" : "+s"(_gb)); _Pragma("unroll") for (int _i = 0; _i < 2; ++_i) \
;         __builtin_amdgcn_global_load_lds((const unsigned*)(_gb + (voff)[_i]), (LAS unsigned*)(lds + (bufoff) + ldsw + _i * 8192), 16, 0, 0); } while (0)
; #define PG8_MMA(ai, bj, At, Bt) do { __builtin_amdgcn_s_setprio(1); _Pragma("unroll") for (int m = 0; m < 4; ++m) _Pragma("unroll") for (int n = 0; n < 2; ++n) _Pragma("unroll") for (int k = 0; k < 2; ++k) \
;         acc[ai][bj][m][n] = __builtin_amdgcn_mfma_f32_16x16x32_bf16(Bt[n][k], At[m][k], acc[ai][bj][m][n], 0, 0, 0); __builtin_amdgcn_s_setprio(0); } while (0)
; #define PG8_WAIT_V(n) asm volatile("s_waitcnt vmcnt(" #n ")" ::: "memory")
; #define PG8_BAR __builtin_amdgcn_s_barrier()
; template <class Epi, class Sched>
; __device__ __forceinline__ void gemm_phase(LAS unsigned char* lds, const Gemm g, const Sched& S, const Epi& E) {
;     ...
;             PG8_STAGE(PG8_SB(1, 1), b3 + hB, voffB);
;             PG8_WAIT_V(6); PG8_BAR; PG8_MMA(1, 1, At, B1); PG8_BAR;
;         }
;     __device__ __forceinline__ void operator()(const f32x4 (&acc)[2][2][4][2], const Unit& u, int wr, int wc, int fr, int fq) const {
;     ...
;         if (u.pn < 12) {
;             const int col0 = u.pn * BM + wc * 32 + 8 * fq;
; #pragma unroll
;             for (int ai = 0; ai < 2; ++ai)
; #pragma unroll
;                 for (int m = 0; m < 4; ++m) { bf16_t* rowp = P0 + (size_t)(row0 + ai * HALF + m * 16) * LDP + col0;
; #pragma unroll
;                     for (int bj = 0; bj < 2; ++bj) { const f32x4 v0 = acc[ai][bj][m][0], v1 = acc[ai][bj][m][1];
;                         u32x4 w; w.x = cvt_pk(v0[0], v0[1]); w.y = cvt_pk(v0[2], v0[3]); w.z = cvt_pk(v1[0], v1[1]); w.w = cvt_pk(v1[2], v1[3]);
;                         *(u32x4*)(rowp + bj * HALF) = w; } }
	s_waitcnt lgkmcnt(0)
	s_setprio 1
	s_waitcnt lgkmcnt(0)
	v_mfma_f32_16x16x32_bf16 v[60:63], v[160:163], v[178:181], v[60:63]
	v_mfma_f32_16x16x32_bf16 v[56:59], v[168:171], v[178:181], v[56:59]
	v_mfma_f32_16x16x32_bf16 v[52:55], v[160:163], v[186:189], v[52:55]
	v_mfma_f32_16x16x32_bf16 v[44:47], v[168:171], v[186:189], v[44:47]
	v_mfma_f32_16x16x32_bf16 v[36:39], v[160:163], v[194:197], v[36:39]
	v_mfma_f32_16x16x32_bf16 v[28:31], v[168:171], v[194:197], v[28:31]
	v_mfma_f32_16x16x32_bf16 v[20:23], v[160:163], v[202:205], v[20:23]
	v_mfma_f32_16x16x32_bf16 v[12:15], v[168:171], v[202:205], v[12:15]
	v_mfma_f32_16x16x32_bf16 v[60:63], v[164:167], v[182:185], v[60:63]
	v_mfma_f32_16x16x32_bf16 v[56:59], v[172:175], v[182:185], v[56:59]
	v_mfma_f32_16x16x32_bf16 v[52:55], v[164:167], v[190:193], v[52:55]
	v_mfma_f32_16x16x32_bf16 v[44:47], v[172:175], v[190:193], v[44:47]
	v_mfma_f32_16x16x32_bf16 v[36:39], v[164:167], v[198:201], v[36:39]
	v_mfma_f32_16x16x32_bf16 v[28:31], v[172:175], v[198:201], v[28:31]
	v_mfma_f32_16x16x32_bf16 v[20:23], v[164:167], v[206:209], v[20:23]
	v_mfma_f32_16x16x32_bf16 v[12:15], v[172:175], v[206:209], v[12:15]
	s_setprio 0
	s_barrier
	s_add_u32 s10, s14, 0x40080
	s_addc_u32 s11, s15, 0
	s_add_i32 s14, s36, s21
	s_mov_b32 m0, s14
	v_lshl_add_u64 v[160:161], s[10:11], 0, v[132:133]
	global_load_lds_dwordx4 v[160:161], off
	v_lshl_add_u64 v[160:161], s[10:11], 0, v[128:129]
	s_add_i32 m0, s14, 0x2000
	s_nop 0
	global_load_lds_dwordx4 v[160:161], off
	s_waitcnt vmcnt(6)
	s_barrier
	s_setprio 1
	v_mfma_f32_16x16x32_bf16 v[48:51], v[210:213], v[178:181], v[48:51]
	v_mfma_f32_16x16x32_bf16 v[40:43], v[218:221], v[178:181], v[40:43]
	v_mfma_f32_16x16x32_bf16 v[32:35], v[210:213], v[186:189], v[32:35]
	v_mfma_f32_16x16x32_bf16 v[24:27], v[218:221], v[186:189], v[24:27]
	v_mfma_f32_16x16x32_bf16 v[16:19], v[210:213], v[194:197], v[16:19]
	v_mfma_f32_16x16x32_bf16 v[8:11], v[218:221], v[194:197], v[8:11]
	v_mfma_f32_16x16x32_bf16 v[4:7], v[210:213], v[202:205], v[4:7]
	v_mfma_f32_16x16x32_bf16 v[0:3], v[218:221], v[202:205], v[0:3]
	v_mfma_f32_16x16x32_bf16 v[48:51], v[214:217], v[182:185], v[48:51]
	v_mfma_f32_16x16x32_bf16 v[40:43], v[222:225], v[182:185], v[40:43]
	v_mfma_f32_16x16x32_bf16 v[32:35], v[214:217], v[190:193], v[32:35]
	v_mfma_f32_16x16x32_bf16 v[24:27], v[222:225], v[190:193], v[24:27]
	v_mfma_f32_16x16x32_bf16 v[16:19], v[214:217], v[198:201], v[16:19]
	v_mfma_f32_16x16x32_bf16 v[8:11], v[222:225], v[198:201], v[8:11]
	v_mfma_f32_16x16x32_bf16 v[4:7], v[214:217], v[206:209], v[4:7]
	v_mfma_f32_16x16x32_bf16 v[0:3], v[222:225], v[206:209], v[0:3]
	s_setprio 0
	s_add_i32 s43, s43, 2
	s_add_u32 s41, s41, 0x100
	s_addc_u32 s42, s42, 0
	s_cmp_gt_u32 s43, 13
	s_mov_b64 s[10:11], s[12:13]
	s_barrier
	s_cbranch_scc0 .LBB0_74
	v_lshl_or_b32 v136, s38, 9, v157
	v_lshl_add_u64 v[160:161], v[138:139], 0, v[136:137]
	v_cvt_pk_bf16_f32 v124, v124, v125
	v_cvt_pk_bf16_f32 v125, v126, v127
	v_cvt_pk_bf16_f32 v126, v120, v121
	v_cvt_pk_bf16_f32 v127, v122, v123
	global_store_dwordx4 v[160:161], v[124:127], off sc1
	v_cvt_pk_bf16_f32 v112, v112, v113
	v_cvt_pk_bf16_f32 v113, v114, v115
	v_cvt_pk_bf16_f32 v114, v104, v105
	v_cvt_pk_bf16_f32 v115, v106, v107
	global_store_dwordx4 v[160:161], v[112:115], off offset:256 sc1
	v_cvt_pk_bf16_f32 v104, v116, v117
	v_cvt_pk_bf16_f32 v105, v118, v119
	v_cvt_pk_bf16_f32 v106, v108, v109
	v_cvt_pk_bf16_f32 v107, v110, v111
	s_cmp_eq_u32 s37, 12
	s_nop 0
	v_lshl_add_u64 v[112:113], v[140:141], 0, v[136:137]
	global_store_dwordx4 v[112:113], v[104:107], off sc1
	v_cvt_pk_bf16_f32 v96, v96, v97
	v_cvt_pk_bf16_f32 v97, v98, v99
	v_cvt_pk_bf16_f32 v98, v88, v89
	v_cvt_pk_bf16_f32 v99, v90, v91
	global_store_dwordx4 v[112:113], v[96:99], off offset:256 sc1
	v_cvt_pk_bf16_f32 v88, v100, v101
	v_cvt_pk_bf16_f32 v89, v102, v103
	v_cvt_pk_bf16_f32 v90, v92, v93
	v_cvt_pk_bf16_f32 v91, v94, v95
	s_mov_b32 s38, s37
	s_nop 0
	v_lshl_add_u64 v[96:97], v[142:143], 0, v[136:137]
	global_store_dwordx4 v[96:97], v[88:91], off sc1
	v_cvt_pk_bf16_f32 v80, v80, v81
	v_cvt_pk_bf16_f32 v81, v82, v83
	v_cvt_pk_bf16_f32 v82, v72, v73
	v_cvt_pk_bf16_f32 v83, v74, v75
	global_store_dwordx4 v[96:97], v[80:83], off offset:256 sc1
	v_cvt_pk_bf16_f32 v72, v84, v85
	v_cvt_pk_bf16_f32 v73, v86, v87
	v_cvt_pk_bf16_f32 v74, v76, v77
	v_cvt_pk_bf16_f32 v75, v78, v79
	s_mov_b64 s[10:11], s[8:9]
	s_nop 0
	v_lshl_add_u64 v[80:81], v[144:145], 0, v[136:137]
	global_store_dwordx4 v[80:81], v[72:75], off sc1
	v_cvt_pk_bf16_f32 v68, v68, v69
	v_cvt_pk_bf16_f32 v69, v70, v71
	v_cvt_pk_bf16_f32 v70, v64, v65
	v_lshl_add_u64 v[64:65], v[146:147], 0, v[136:137]
	v_cvt_pk_bf16_f32 v71, v66, v67
	global_store_dwordx4 v[80:81], v[68:71], off offset:256 sc1
	v_cvt_pk_bf16_f32 v60, v60, v61
	v_cvt_pk_bf16_f32 v61, v62, v63
	v_cvt_pk_bf16_f32 v62, v56, v57
	v_cvt_pk_bf16_f32 v63, v58, v59
	global_store_dwordx4 v[64:65], v[60:63], off sc1
	v_cvt_pk_bf16_f32 v48, v48, v49
	v_cvt_pk_bf16_f32 v49, v50, v51
	v_cvt_pk_bf16_f32 v50, v40, v41
	v_cvt_pk_bf16_f32 v51, v42, v43
	global_store_dwordx4 v[64:65], v[48:51], off offset:256 sc1
	v_cvt_pk_bf16_f32 v40, v52, v53
	v_cvt_pk_bf16_f32 v41, v54, v55
	v_cvt_pk_bf16_f32 v42, v44, v45
	v_cvt_pk_bf16_f32 v43, v46, v47
	s_nop 1
	v_lshl_add_u64 v[48:49], v[148:149], 0, v[136:137]
	global_store_dwordx4 v[48:49], v[40:43], off sc1
	v_cvt_pk_bf16_f32 v32, v32, v33
	v_cvt_pk_bf16_f32 v33, v34, v35
	v_cvt_pk_bf16_f32 v34, v24, v25
	v_cvt_pk_bf16_f32 v35, v26, v27
	global_store_dwordx4 v[48:49], v[32:35], off offset:256 sc1
	v_cvt_pk_bf16_f32 v24, v36, v37
	v_cvt_pk_bf16_f32 v25, v38, v39
	v_cvt_pk_bf16_f32 v26, v28, v29
	v_cvt_pk_bf16_f32 v27, v30, v31
	s_nop 1
	v_lshl_add_u64 v[32:33], v[150:151], 0, v[136:137]
	global_store_dwordx4 v[32:33], v[24:27], off sc1
	v_cvt_pk_bf16_f32 v16, v16, v17
	v_cvt_pk_bf16_f32 v17, v18, v19
	v_cvt_pk_bf16_f32 v18, v8, v9
	v_cvt_pk_bf16_f32 v19, v10, v11
	global_store_dwordx4 v[32:33], v[16:19], off offset:256 sc1
	v_cvt_pk_bf16_f32 v8, v20, v21
	v_cvt_pk_bf16_f32 v9, v22, v23
	v_cvt_pk_bf16_f32 v10, v12, v13
	v_cvt_pk_bf16_f32 v11, v14, v15
	s_nop 1
	v_lshl_add_u64 v[16:17], v[152:153], 0, v[136:137]
	global_store_dwordx4 v[16:17], v[8:11], off sc1
	v_cvt_pk_bf16_f32 v4, v4, v5
	v_cvt_pk_bf16_f32 v5, v6, v7
	v_cvt_pk_bf16_f32 v6, v0, v1
	v_cvt_pk_bf16_f32 v7, v2, v3
	global_store_dwordx4 v[16:17], v[4:7], off offset:256 sc1
	s_cbranch_scc0 .LBB0_73
	s_waitcnt vmcnt(0)
	s_cmpk_gt_u32 s20, 0xff
	s_cbranch_scc1 .LBB0_78
	s_barrier
